# P0 s5mat: MF Toeplitz half branch-free with b128 LDS reads instead of 16 exec-masked scalar reads each with a wait
# speedup vs baseline: 1.0165x; 1.0030x over previous
.LBB0_46:
	s_or_b64 exec, exec, s[0:1]
	s_mov_b64 s[24:25], exec
	v_readlane_b32 s0, v254, 27
	v_readlane_b32 s1, v254, 28
	s_and_b64 s[0:1], s[24:25], s[0:1]
	s_mov_b64 exec, s[0:1]
	s_cbranch_execz .LBB0_101
	s_lshl_b64 s[0:1], s[86:87], 10
	v_readlane_b32 s4, v254, 33
	s_add_u32 s30, s4, s0
	s_addc_u32 s31, s58, s1
	s_lshl_b32 s86, s52, 4
	v_bfe_u32 v49, v62, 6, 4
	v_or_b32_e32 v48, s86, v49
	v_lshlrev_b32_e32 v48, 2, v48
	global_load_dword v46, v48, s[82:83]
	v_xor_b32_e32 v48, 32, v48
	global_load_dword v47, v48, s[82:83]
	s_waitcnt vmcnt(0)
	s_mov_b64 s[52:53], 0
	v_mov_b32_e32 v6, v65
	v_mov_b32_e32 v7, v62
	s_branch .LBB0_50

.LBB0_52:
	s_andn2_saveexec_b64 s[54:55], s[0:1]
	s_cbranch_execz .LBB0_49
	v_lshrrev_b32_e32 v9, 4, v8
	v_sub_u32_e32 v3, v4, v9
	v_lshlrev_b32_e32 v3, 10, v3
	v_and_b32_e32 v13, 8, v6
	v_add3_u32 v10, 0, v3, v5
	v_lshl_add_u32 v14, v13, 2, v10
	v_sub_u32_e32 v10, v9, v4
	v_lshlrev_b32_e32 v10, 10, v10
	s_add_i32 s0, 0, 0x10400
	v_add3_u32 v10, s0, v10, v5
	v_lshl_add_u32 v15, v13, 2, v10
	ds_read_b128 v[20:23], v14 offset:50176
	ds_read_b128 v[24:27], v14 offset:50192
	ds_read_b128 v[28:31], v15
	ds_read_b128 v[16:19], v15 offset:16
	v_cmp_ge_i32_e32 vcc, v4, v9
	v_cmp_ge_i32_e64 s[20:21], v9, v4
	v_cmp_eq_u32_e64 s[22:23], v4, v9
	v_cmp_eq_u32_e64 s[34:35], v12, v49
	v_sub_u32_e32 v51, v12, v13
	s_nop 1
	v_cndmask_b32_e64 v50, v47, v46, s[34:35]
	v_cndmask_b32_e64 v50, 0, v50, s[22:23]
	s_waitcnt lgkmcnt(0)
	v_cndmask_b32_e32 v3, 0, v20, vcc
	v_cndmask_b32_e64 v28, 0, v28, s[20:21]
	v_add_f32_e32 v3, v3, v28
	v_cndmask_b32_e32 v9, 0, v21, vcc
	v_cndmask_b32_e64 v29, 0, v29, s[20:21]
	v_add_f32_e32 v9, v9, v29
	v_cndmask_b32_e32 v10, 0, v22, vcc
	v_cndmask_b32_e64 v30, 0, v30, s[20:21]
	v_add_f32_e32 v10, v10, v30
	v_cndmask_b32_e32 v11, 0, v23, vcc
	v_cndmask_b32_e64 v31, 0, v31, s[20:21]
	v_add_f32_e32 v11, v11, v31
	v_cndmask_b32_e32 v24, 0, v24, vcc
	v_cndmask_b32_e64 v16, 0, v16, s[20:21]
	v_add_f32_e32 v16, v24, v16
	v_cndmask_b32_e32 v25, 0, v25, vcc
	v_cndmask_b32_e64 v17, 0, v17, s[20:21]
	v_add_f32_e32 v17, v25, v17
	v_cndmask_b32_e32 v26, 0, v26, vcc
	v_cndmask_b32_e64 v18, 0, v18, s[20:21]
	v_add_f32_e32 v18, v26, v18
	v_cndmask_b32_e32 v27, 0, v27, vcc
	v_cndmask_b32_e64 v19, 0, v19, s[20:21]
	v_add_f32_e32 v19, v27, v19
	v_cmp_eq_u32_e32 vcc, 0, v51
	s_nop 1
	v_cndmask_b32_e32 v20, 0, v50, vcc
	v_add_f32_e32 v3, v3, v20
	v_cmp_eq_u32_e32 vcc, 1, v51
	s_nop 1
	v_cndmask_b32_e32 v20, 0, v50, vcc
	v_add_f32_e32 v9, v9, v20
	v_cmp_eq_u32_e32 vcc, 2, v51
	s_nop 1
	v_cndmask_b32_e32 v20, 0, v50, vcc
	v_add_f32_e32 v10, v10, v20
	v_cmp_eq_u32_e32 vcc, 3, v51
	s_nop 1
	v_cndmask_b32_e32 v20, 0, v50, vcc
	v_add_f32_e32 v11, v11, v20
	v_cmp_eq_u32_e32 vcc, 4, v51
	s_nop 1
	v_cndmask_b32_e32 v20, 0, v50, vcc
	v_add_f32_e32 v16, v16, v20
	v_cmp_eq_u32_e32 vcc, 5, v51
	s_nop 1
	v_cndmask_b32_e32 v20, 0, v50, vcc
	v_add_f32_e32 v17, v17, v20
	v_cmp_eq_u32_e32 vcc, 6, v51
	s_nop 1
	v_cndmask_b32_e32 v20, 0, v50, vcc
	v_add_f32_e32 v18, v18, v20
	v_cmp_eq_u32_e32 vcc, 7, v51
	s_nop 1
	v_cndmask_b32_e32 v20, 0, v50, vcc
	v_add_f32_e32 v19, v19, v20
	s_branch .LBB0_49
